# diff attention: loop-invariant V-tile LDS base addresses hoisted out of the key-tile loop
# speedup vs baseline: 1.0324x; 1.0020x over previous
.LBB0_1309:
	s_or_b32 s2, s2, s37
	s_or_b32 s42, s2, 0xa20
	v_mov_b32_e32 v34, v224
	s_lshl_b64 s[10:11], s[2:3], 1
	s_add_u32 s10, s30, s10
	v_bfe_u32 v16, v34, 4, 2
	s_addc_u32 s11, s31, s11
	v_lshlrev_b32_e32 v0, 4, v16
	v_and_b32_e32 v35, 15, v34
	v_lshl_add_u64 v[2:3], s[10:11], 0, v[0:1]
	s_mov_b64 s[10:11], 0x1040
	v_add_u32_e32 v12, v35, v142
	v_lshl_add_u64 v[10:11], v[2:3], 0, s[10:11]
	v_mad_i64_i32 v[6:7], s[10:11], v12, s6, v[10:11]
	global_load_dwordx4 v[2:5], v[6:7], off
	s_nop 0
	global_load_dwordx4 v[6:9], v[6:7], off offset:64
	v_add_u32_e32 v24, 0x100, v34
	v_ashrrev_i32_e32 v150, 3, v34
	v_ashrrev_i32_e32 v151, 3, v24
	v_mov_b64_e32 v[18:19], s[30:31]
	s_mov_b32 s43, s3
	v_lshlrev_b32_e32 v17, 4, v34
	v_lshlrev_b32_e32 v36, 3, v16
	v_add_u32_e32 v16, s44, v150
	v_add_u32_e32 v26, s44, v151
	s_lshl_b64 s[42:43], s[42:43], 1
	v_and_b32_e32 v20, 0x70, v17
	v_mad_i64_i32 v[16:17], s[10:11], v16, s6, v[18:19]
	v_mad_i64_i32 v[18:19], s[10:11], v26, s6, v[18:19]
	v_add_u32_e32 v12, 16, v12
	v_mov_b32_e32 v21, v1
	v_lshl_add_u64 v[24:25], v[16:17], 0, s[42:43]
	v_lshl_add_u64 v[18:19], v[18:19], 0, s[42:43]
	v_mad_i64_i32 v[14:15], s[10:11], v12, s6, v[10:11]
	v_lshl_add_u64 v[24:25], v[24:25], 0, v[20:21]
	v_lshl_add_u64 v[18:19], v[18:19], 0, v[20:21]
	global_load_dwordx4 v[10:13], v[14:15], off
	v_mov_b64_e32 v[22:23], s[0:1]
	global_load_dwordx4 v[14:17], v[14:15], off offset:64
	s_nop 0
	global_load_dwordx4 v[84:87], v[24:25], off
	global_load_dwordx4 v[88:91], v[18:19], off
	s_mov_b32 s39, s3
	v_add_u32_e32 v152, 16, v0
	s_movk_i32 s2, 0x100
	v_mul_u32_u24_e32 v153, 0x90, v35
	v_mov_b32_e32 v160, 0
	v_mov_b32_e32 v161, 0xf149f2ca
	v_mov_b32_e32 v159, 0xf149f2ca
	s_waitcnt vmcnt(5)
	v_lshlrev_b32_e32 v18, 16, v2
	v_and_b32_e32 v19, 0xffff0000, v2
	v_lshlrev_b32_e32 v2, 16, v3
	v_and_b32_e32 v3, 0xffff0000, v3
	v_lshlrev_b32_e32 v24, 16, v4
	v_and_b32_e32 v25, 0xffff0000, v4
	v_lshlrev_b32_e32 v4, 16, v5
	v_and_b32_e32 v5, 0xffff0000, v5
	s_waitcnt vmcnt(4)
	v_lshlrev_b32_e32 v26, 16, v6
	v_and_b32_e32 v27, 0xffff0000, v6
	v_lshlrev_b32_e32 v6, 16, v7
	v_and_b32_e32 v7, 0xffff0000, v7
	v_pk_mul_f32 v[2:3], v[2:3], s[28:29] op_sel_hi:[1,0]
	v_lshlrev_b32_e32 v28, 16, v8
	v_and_b32_e32 v29, 0xffff0000, v8
	v_lshlrev_b32_e32 v8, 16, v9
	v_and_b32_e32 v9, 0xffff0000, v9
	v_pk_mul_f32 v[4:5], v[4:5], s[28:29] op_sel_hi:[1,0]
	v_pk_mul_f32 v[6:7], v[6:7], s[28:29] op_sel_hi:[1,0]
	v_cvt_pk_bf16_f32 v73, v2, v3
	v_mad_i64_i32 v[2:3], s[10:11], v150, s97, v[22:23]
	v_pk_mul_f32 v[8:9], v[8:9], s[28:29] op_sel_hi:[1,0]
	v_cvt_pk_bf16_f32 v75, v4, v5
	v_cvt_pk_bf16_f32 v69, v6, v7
	v_lshl_add_u64 v[4:5], v[2:3], 0, s[38:39]
	v_mad_i64_i32 v[6:7], s[10:11], v151, s97, v[22:23]
	v_cvt_pk_bf16_f32 v71, v8, v9
	v_lshl_add_u64 v[4:5], v[4:5], 0, v[20:21]
	v_lshl_add_u64 v[8:9], v[6:7], 0, s[38:39]
	v_pk_mul_f32 v[18:19], v[18:19], s[28:29] op_sel_hi:[1,0]
	v_pk_mul_f32 v[24:25], v[24:25], s[28:29] op_sel_hi:[1,0]
	v_lshl_add_u64 v[8:9], v[8:9], 0, v[20:21]
	global_load_dwordx4 v[92:95], v[4:5], off
	global_load_dwordx4 v[96:99], v[8:9], off
	v_add_u32_e32 v4, 0x200, v34
	v_cvt_pk_bf16_f32 v72, v18, v19
	v_cvt_pk_bf16_f32 v74, v24, v25
	v_ashrrev_i32_e32 v24, 3, v4
	v_add_u32_e32 v18, 0x300, v34
	v_mad_i64_i32 v[4:5], s[10:11], v24, s97, v[22:23]
	v_ashrrev_i32_e32 v25, 3, v18
	v_lshl_add_u64 v[8:9], v[4:5], 0, s[38:39]
	v_mad_i64_i32 v[18:19], s[10:11], v25, s97, v[22:23]
	v_lshl_add_u64 v[8:9], v[8:9], 0, v[20:21]
	v_lshl_add_u64 v[22:23], v[18:19], 0, s[38:39]
	v_lshl_add_u64 v[22:23], v[22:23], 0, v[20:21]
	global_load_dwordx4 v[100:103], v[8:9], off
	global_load_dwordx4 v[104:107], v[22:23], off
	v_lshl_add_u64 v[132:133], v[2:3], 0, v[20:21]
	v_and_b32_e32 v3, 64, v231
	v_xor_b32_e32 v2, 16, v231
	v_add_u32_e32 v143, 64, v3
	v_cmp_lt_i32_e32 vcc, v2, v143
	s_waitcnt vmcnt(7)
	v_lshlrev_b32_e32 v30, 16, v10
	v_and_b32_e32 v31, 0xffff0000, v10
	v_cndmask_b32_e32 v2, v231, v2, vcc
	v_lshlrev_b32_e32 v149, 2, v2
	v_xor_b32_e32 v2, 32, v231
	v_lshlrev_b32_e32 v10, 16, v11
	v_and_b32_e32 v11, 0xffff0000, v11
	v_lshlrev_b32_e32 v32, 16, v12
	v_and_b32_e32 v33, 0xffff0000, v12
	v_lshlrev_b32_e32 v12, 16, v13
	v_and_b32_e32 v13, 0xffff0000, v13
	v_cmp_lt_i32_e32 vcc, v2, v143
	v_pk_mul_f32 v[10:11], v[10:11], s[28:29] op_sel_hi:[1,0]
	v_pk_mul_f32 v[12:13], v[12:13], s[28:29] op_sel_hi:[1,0]
	s_waitcnt vmcnt(6)
	v_lshlrev_b32_e32 v8, 16, v14
	v_and_b32_e32 v9, 0xffff0000, v14
	v_cndmask_b32_e32 v2, v231, v2, vcc
	v_cvt_pk_bf16_f32 v77, v10, v11
	v_cvt_pk_bf16_f32 v79, v12, v13
	v_pk_mul_f32 v[8:9], v[8:9], s[28:29] op_sel_hi:[1,0]
	v_lshlrev_b32_e32 v10, 16, v15
	v_and_b32_e32 v11, 0xffff0000, v15
	v_lshlrev_b32_e32 v12, 16, v16
	v_and_b32_e32 v13, 0xffff0000, v16
	v_lshlrev_b32_e32 v14, 16, v17
	v_and_b32_e32 v15, 0xffff0000, v17
	s_add_u32 s10, s30, s42
	v_lshlrev_b32_e32 v148, 2, v2
	v_lshlrev_b32_e32 v2, 2, v231
	v_pk_mul_f32 v[26:27], v[26:27], s[28:29] op_sel_hi:[1,0]
	v_pk_mul_f32 v[28:29], v[28:29], s[28:29] op_sel_hi:[1,0]
	v_pk_mul_f32 v[30:31], v[30:31], s[28:29] op_sel_hi:[1,0]
	v_pk_mul_f32 v[32:33], v[32:33], s[28:29] op_sel_hi:[1,0]
	v_pk_mul_f32 v[10:11], v[10:11], s[28:29] op_sel_hi:[1,0]
	v_pk_mul_f32 v[12:13], v[12:13], s[28:29] op_sel_hi:[1,0]
	v_pk_mul_f32 v[14:15], v[14:15], s[28:29] op_sel_hi:[1,0]
	v_cvt_pk_bf16_f32 v80, v8, v9
	v_add_u32_e32 v8, 16, v20
	s_addc_u32 s11, s31, s43
	v_lshl_add_u64 v[134:135], v[6:7], 0, v[20:21]
	v_lshl_add_u64 v[136:137], v[4:5], 0, v[20:21]
	v_sub_u32_e32 v4, v152, v36
	v_mul_lo_u32 v5, v150, s60
	v_mul_lo_u32 v6, v151, s60
	v_mul_lo_u32 v7, v24, s60
	v_mul_lo_u32 v9, v25, s60
	v_and_or_b32 v146, v2, s2, v0
	v_mov_b32_e32 v2, v1
	v_mov_b32_e32 v3, v1
	v_cvt_pk_bf16_f32 v68, v26, v27
	v_cvt_pk_bf16_f32 v70, v28, v29
	v_cvt_pk_bf16_f32 v76, v30, v31
	v_cvt_pk_bf16_f32 v78, v32, v33
	v_cvt_pk_bf16_f32 v81, v10, v11
	v_cvt_pk_bf16_f32 v82, v12, v13
	v_cvt_pk_bf16_f32 v83, v14, v15
	v_lshl_add_u64 v[130:131], s[10:11], 0, v[20:21]
	v_lshl_add_u64 v[138:139], v[18:19], 0, v[20:21]
	v_mov_b32_e32 v0, v1
	v_add_u32_e32 v154, v8, v5
	v_add_u32_e32 v155, v8, v6
	v_add_u32_e32 v156, v8, v7
	v_add_u32_e32 v157, v8, v9
	v_add_u32_e32 v158, v4, v153
	v_mov_b64_e32 v[6:7], v[2:3]
	v_mov_b64_e32 v[10:11], v[2:3]
	v_mov_b64_e32 v[22:23], v[2:3]
	v_mov_b64_e32 v[30:31], v[2:3]
	v_mov_b64_e32 v[38:39], v[2:3]
	v_mov_b64_e32 v[46:47], v[2:3]
	v_mov_b64_e32 v[54:55], v[2:3]
	v_mov_b64_e32 v[62:63], v[2:3]
	v_mov_b64_e32 v[14:15], v[2:3]
	v_mov_b64_e32 v[18:19], v[2:3]
	v_mov_b64_e32 v[26:27], v[2:3]
	v_mov_b64_e32 v[34:35], v[2:3]
	v_mov_b64_e32 v[42:43], v[2:3]
	v_mov_b64_e32 v[50:51], v[2:3]
	v_mov_b64_e32 v[58:59], v[2:3]
	v_mov_b64_e32 v[66:67], v[2:3]
	v_or_b32_e32 v147, 4, v146
	v_or_b32_e32 v144, 8, v146
	v_or_b32_e32 v145, 12, v146
	v_mov_b64_e32 v[4:5], v[0:1]
	v_mov_b64_e32 v[8:9], v[0:1]
	v_mov_b64_e32 v[20:21], v[0:1]
	v_mov_b64_e32 v[28:29], v[0:1]
	v_mov_b64_e32 v[36:37], v[0:1]
	v_mov_b64_e32 v[44:45], v[0:1]
	v_mov_b64_e32 v[52:53], v[0:1]
	v_mov_b64_e32 v[60:61], v[0:1]
	v_mov_b64_e32 v[12:13], v[0:1]
	v_mov_b64_e32 v[16:17], v[0:1]
	v_mov_b64_e32 v[24:25], v[0:1]
	v_mov_b64_e32 v[32:33], v[0:1]
	v_mov_b64_e32 v[40:41], v[0:1]
	v_mov_b64_e32 v[48:49], v[0:1]
	v_mov_b64_e32 v[56:57], v[0:1]
	v_mov_b64_e32 v[64:65], v[0:1]
	v_mov_b32_e32 v0, 0
	s_mov_b32 s2, 0
	v_add_u32_e32 v185, 0x2000, v158
	v_add_u32_e32 v186, 0x2800, v158
	v_add_u32_e32 v187, 0x3000, v158
	v_add_u32_e32 v188, 0x6000, v158
	v_add_u32_e32 v189, 0x3800, v158
	v_add_u32_e32 v190, 0x4800, v158
	v_add_u32_e32 v191, 0x5000, v158
	v_add_u32_e32 v192, 0x5800, v158

.LBB0_1314:
	v_fmac_f32_e32 v3, v0, v169
	v_cvt_pk_bf16_f32 v168, v167, v168
	v_cvt_pk_bf16_f32 v169, v170, v171
	v_cvt_pk_bf16_f32 v170, v172, v173
	v_cvt_pk_bf16_f32 v171, v174, v175
	v_cvt_pk_bf16_f32 v172, v108, v109
	v_cvt_pk_bf16_f32 v173, v110, v111
	v_cvt_pk_bf16_f32 v174, v112, v113
	v_cvt_pk_bf16_f32 v175, v114, v177
	ds_read2_b64 v[108:111], v185 offset0:128 offset1:132
	s_waitcnt lgkmcnt(1)
	s_waitcnt lgkmcnt(0)
	v_mfma_f32_16x16x32_bf16 v[64:67], v[168:171], v[108:111], v[64:67]
	v_fmac_f32_e32 v115, v160, v161
	v_cvt_pk_bf16_f32 v160, v125, v126
	v_cvt_pk_bf16_f32 v161, v127, v162
	v_mfma_f32_16x16x32_bf16 v[60:63], v[172:175], v[108:111], v[60:63]
	ds_read2_b64 v[110:113], v186 offset0:160 offset1:164
	v_cvt_pk_bf16_f32 v162, v163, v164
	v_cvt_pk_bf16_f32 v163, v165, v166
	v_cvt_pk_bf16_f32 v116, v116, v117
	v_cvt_pk_bf16_f32 v117, v118, v119
	v_cvt_pk_bf16_f32 v118, v120, v121
	v_cvt_pk_bf16_f32 v119, v122, v123
	ds_read2_b64 v[120:123], v185 offset0:136 offset1:140
	s_waitcnt lgkmcnt(1)
	v_mfma_f32_16x16x32_bf16 v[56:59], v[168:171], v[110:113], v[56:59]
	s_add_i32 s10, s45, s2
	s_cmp_eq_u32 s10, 3
	v_mfma_f32_16x16x32_bf16 v[52:55], v[172:175], v[110:113], v[52:55]
	ds_read2_b64 v[110:113], v187 offset0:192 offset1:196
	s_waitcnt lgkmcnt(1)
	v_mfma_f32_16x16x32_bf16 v[64:67], v[160:163], v[120:123], v[64:67]
	v_mfma_f32_16x16x32_bf16 v[60:63], v[116:119], v[120:123], v[60:63]
	ds_read2_b64 v[120:123], v186 offset0:168 offset1:172
	s_waitcnt lgkmcnt(1)
	v_mfma_f32_16x16x32_bf16 v[48:51], v[168:171], v[110:113], v[48:51]
	v_mfma_f32_16x16x32_bf16 v[44:47], v[172:175], v[110:113], v[44:47]
	ds_read2_b64 v[176:179], v189 offset0:224 offset1:228
	s_waitcnt lgkmcnt(1)
	v_mfma_f32_16x16x32_bf16 v[56:59], v[160:163], v[120:123], v[56:59]
	v_mfma_f32_16x16x32_bf16 v[52:55], v[116:119], v[120:123], v[52:55]
	ds_read2_b64 v[120:123], v187 offset0:200 offset1:204
	s_waitcnt lgkmcnt(0)
	v_mfma_f32_16x16x32_bf16 v[48:51], v[160:163], v[120:123], v[48:51]
	v_mfma_f32_16x16x32_bf16 v[44:47], v[116:119], v[120:123], v[44:47]
	ds_read2_b64 v[120:123], v189 offset0:232 offset1:236
	v_mfma_f32_16x16x32_bf16 v[40:43], v[168:171], v[176:179], v[40:43]
	v_mfma_f32_16x16x32_bf16 v[36:39], v[172:175], v[176:179], v[36:39]
	ds_read2_b64 v[176:179], v190 offset1:4
	s_waitcnt lgkmcnt(1)
	v_mfma_f32_16x16x32_bf16 v[40:43], v[160:163], v[120:123], v[40:43]
	v_mfma_f32_16x16x32_bf16 v[36:39], v[116:119], v[120:123], v[36:39]
	ds_read2_b64 v[120:123], v190 offset0:8 offset1:12
	s_waitcnt lgkmcnt(1)
	v_mfma_f32_16x16x32_bf16 v[32:35], v[168:171], v[176:179], v[32:35]
	v_mfma_f32_16x16x32_bf16 v[28:31], v[172:175], v[176:179], v[28:31]
	ds_read2_b64 v[176:179], v191 offset0:32 offset1:36
	s_waitcnt lgkmcnt(1)
	v_mfma_f32_16x16x32_bf16 v[32:35], v[160:163], v[120:123], v[32:35]
	v_mfma_f32_16x16x32_bf16 v[28:31], v[116:119], v[120:123], v[28:31]
	ds_read2_b64 v[120:123], v191 offset0:40 offset1:44
	s_waitcnt lgkmcnt(1)
	v_mfma_f32_16x16x32_bf16 v[24:27], v[168:171], v[176:179], v[24:27]
	v_mfma_f32_16x16x32_bf16 v[20:23], v[172:175], v[176:179], v[20:23]
	ds_read2_b64 v[176:179], v192 offset0:64 offset1:68
	s_waitcnt lgkmcnt(1)
	v_mfma_f32_16x16x32_bf16 v[24:27], v[160:163], v[120:123], v[24:27]
	v_mfma_f32_16x16x32_bf16 v[20:23], v[116:119], v[120:123], v[20:23]
	ds_read2_b64 v[120:123], v192 offset0:72 offset1:76
	s_waitcnt lgkmcnt(1)
	v_mfma_f32_16x16x32_bf16 v[16:19], v[168:171], v[176:179], v[16:19]
	v_mfma_f32_16x16x32_bf16 v[8:11], v[172:175], v[176:179], v[8:11]
	ds_read2_b64 v[176:179], v188 offset0:96 offset1:100
	s_waitcnt lgkmcnt(1)
	v_mfma_f32_16x16x32_bf16 v[16:19], v[160:163], v[120:123], v[16:19]
	v_mfma_f32_16x16x32_bf16 v[8:11], v[116:119], v[120:123], v[8:11]
	ds_read2_b64 v[120:123], v188 offset0:104 offset1:108
	s_waitcnt lgkmcnt(1)
	v_mfma_f32_16x16x32_bf16 v[12:15], v[168:171], v[176:179], v[12:15]
	v_mfma_f32_16x16x32_bf16 v[4:7], v[172:175], v[176:179], v[4:7]
	s_waitcnt lgkmcnt(0)
	v_mfma_f32_16x16x32_bf16 v[12:15], v[160:163], v[120:123], v[12:15]
	v_mfma_f32_16x16x32_bf16 v[4:7], v[116:119], v[120:123], v[4:7]
	s_cbranch_scc1 .LBB0_1316
	v_mov_b32_e32 v161, v124
	v_mov_b32_e32 v160, v115
	v_mov_b32_e32 v0, v3
	s_branch .LBB0_1310

.LBB0_1320:
	s_waitcnt lgkmcnt(0)
	v_fmac_f32_e32 v84, v115, v102
	v_mov_b32_e32 v115, v100
	v_fmac_f32_e32 v115, v3, v80
	v_cvt_pk_bf16_f32 v80, v79, v81
	v_cvt_pk_bf16_f32 v81, v82, v83
	v_cvt_pk_bf16_f32 v82, v96, v97
	v_cvt_pk_bf16_f32 v83, v98, v99
	v_cvt_pk_bf16_f32 v92, v92, v93
	v_cvt_pk_bf16_f32 v93, v94, v95
	v_cvt_pk_bf16_f32 v94, v103, v89
	v_cvt_pk_bf16_f32 v95, v90, v91
	ds_read2_b64 v[96:99], v185 offset0:128 offset1:132
	s_waitcnt lgkmcnt(0)
	v_mfma_f32_16x16x32_bf16 v[64:67], v[80:83], v[96:99], v[64:67]
	v_cvt_pk_bf16_f32 v72, v2, v72
	v_cvt_pk_bf16_f32 v73, v73, v74
	v_cvt_pk_bf16_f32 v74, v75, v76
	v_mfma_f32_16x16x32_bf16 v[60:63], v[92:95], v[96:99], v[60:63]
	ds_read2_b64 v[96:99], v186 offset0:160 offset1:164
	v_cvt_pk_bf16_f32 v75, v77, v78
	v_cvt_pk_bf16_f32 v76, v88, v85
	s_waitcnt lgkmcnt(0)
	v_mfma_f32_16x16x32_bf16 v[56:59], v[80:83], v[96:99], v[56:59]
	v_cvt_pk_bf16_f32 v77, v86, v87
	v_cvt_pk_bf16_f32 v78, v68, v69
	v_cvt_pk_bf16_f32 v79, v70, v71
	v_mfma_f32_16x16x32_bf16 v[52:55], v[92:95], v[96:99], v[52:55]
	ds_read2_b64 v[96:99], v187 offset0:192 offset1:196
	s_mov_b64 s[42:43], -1
	s_waitcnt lgkmcnt(0)
	v_mfma_f32_16x16x32_bf16 v[48:51], v[80:83], v[96:99], v[48:51]
	v_mfma_f32_16x16x32_bf16 v[44:47], v[92:95], v[96:99], v[44:47]
	ds_read2_b64 v[96:99], v189 offset0:224 offset1:228
	s_waitcnt lgkmcnt(0)
	v_mfma_f32_16x16x32_bf16 v[100:103], v[80:83], v[96:99], v[40:43]
	v_mfma_f32_16x16x32_bf16 v[96:99], v[92:95], v[96:99], v[36:39]
	s_nop 2
	ds_read2_b64 v[36:39], v190 offset1:4
	s_waitcnt lgkmcnt(0)
	v_mfma_f32_16x16x32_bf16 v[104:107], v[80:83], v[36:39], v[32:35]
	s_nop 2
	ds_read2_b64 v[32:35], v191 offset0:32 offset1:36
	s_waitcnt lgkmcnt(0)
	v_mfma_f32_16x16x32_bf16 v[116:119], v[92:95], v[32:35], v[20:23]
	s_nop 2
	ds_read2_b64 v[20:23], v192 offset0:64 offset1:68
	s_waitcnt lgkmcnt(0)
	v_mfma_f32_16x16x32_bf16 v[124:127], v[92:95], v[20:23], v[8:11]
	s_nop 2
	ds_read2_b64 v[8:11], v188 offset0:96 offset1:100
	v_mfma_f32_16x16x32_bf16 v[28:31], v[92:95], v[36:39], v[28:31]
	v_mfma_f32_16x16x32_bf16 v[24:27], v[80:83], v[32:35], v[24:27]
	v_mfma_f32_16x16x32_bf16 v[120:123], v[80:83], v[20:23], v[16:19]
	s_waitcnt lgkmcnt(0)
	v_mfma_f32_16x16x32_bf16 v[80:83], v[80:83], v[8:11], v[12:15]
	s_nop 0
	ds_read2_b64 v[18:21], v190 offset0:8 offset1:12
	v_mfma_f32_16x16x32_bf16 v[90:93], v[92:95], v[8:11], v[4:7]
	ds_read2_b64 v[10:13], v187 offset0:200 offset1:204
	ds_read2_b64 v[14:17], v189 offset0:232 offset1:236
	s_nop 0
	ds_read2_b64 v[6:9], v186 offset0:168 offset1:172
	ds_read2_b64 v[2:5], v185 offset0:136 offset1:140
	v_mov_b32_e32 v184, v115
	s_nop 1
	v_permlane16_swap_b32 v184, v115
	v_add_f32_e32 v115, v115, v184
	v_mov_b32_e32 v184, v115
	s_nop 1
	v_permlane32_swap_b32 v184, v115
	v_add_f32_e32 v115, v115, v184
	v_div_scale_f32 v0, s[10:11], v115, v115, 1.0
	s_waitcnt lgkmcnt(1)
	v_mfma_f32_16x16x32_bf16 v[38:41], v[72:75], v[6:9], v[56:59]
	v_mfma_f32_16x16x32_bf16 v[6:9], v[76:79], v[6:9], v[52:55]
	s_nop 2
	v_rcp_f32_e32 v54, v0
	v_mfma_f32_16x16x32_bf16 v[50:53], v[72:75], v[10:13], v[48:51]
	v_fma_f32 v55, -v0, v54, 1.0
	v_fmac_f32_e32 v54, v55, v54
	v_div_scale_f32 v55, vcc, 1.0, v115, 1.0
	v_mul_f32_e32 v56, v55, v54
	v_fma_f32 v57, -v0, v56, v55
	v_mfma_f32_16x16x32_bf16 v[10:13], v[76:79], v[10:13], v[44:47]
	v_fmac_f32_e32 v56, v57, v54
	v_fma_f32 v0, -v0, v56, v55
	v_div_fmas_f32 v0, v0, v54, v56
	v_mfma_f32_16x16x32_bf16 v[46:49], v[72:75], v[18:21], v[104:107]
	v_div_fixup_f32 v0, v0, v115, 1.0
	ds_bpermute_b32 v54, v146, v0
	ds_bpermute_b32 v55, v147, v0
	v_mfma_f32_16x16x32_bf16 v[18:21], v[76:79], v[18:21], v[28:31]
	s_nop 2
	ds_read2_b64 v[28:31], v191 offset0:40 offset1:44
	s_waitcnt lgkmcnt(3)
	v_mfma_f32_16x16x32_bf16 v[34:37], v[72:75], v[2:5], v[64:67]
	s_waitcnt lgkmcnt(1)
	v_pk_mul_f32 v[56:57], v[46:47], v[54:55]
	s_waitcnt lgkmcnt(0)
	v_mfma_f32_16x16x32_bf16 v[86:89], v[72:75], v[28:31], v[24:27]
	v_mul_f32_e64 v64, v50, v54
	v_mul_f32_e64 v65, v51, v55
	v_mfma_f32_16x16x32_bf16 v[22:25], v[76:79], v[28:31], v[116:119]
	ds_read2_b64 v[26:29], v192 offset0:72 offset1:76
	ds_read2_b64 v[30:33], v188 offset0:104 offset1:108
	s_nop 2
	v_pk_mul_f32 v[58:59], v[86:87], v[54:55]
	v_mfma_f32_16x16x32_bf16 v[2:5], v[76:79], v[2:5], v[60:63]
	s_nop 2
	v_mul_f32_e64 v60, v34, v54
	v_mul_f32_e64 v61, v35, v55
	ds_bpermute_b32 v34, v144, v0
	ds_bpermute_b32 v35, v145, v0
	v_mfma_f32_16x16x32_bf16 v[42:45], v[72:75], v[14:17], v[100:103]
	v_mov_b32_e32 v184, v84
	s_nop 1
	v_permlane16_swap_b32 v184, v84
	v_add_f32_e32 v84, v84, v184
	v_mov_b32_e32 v184, v84
	s_nop 1
	v_permlane32_swap_b32 v184, v84
	v_add_f32_e32 v84, v84, v184
	v_div_scale_f32 v0, s[10:11], v84, v84, 1.0
	v_pk_mul_f32 v[62:63], v[38:39], v[54:55]
	v_mfma_f32_16x16x32_bf16 v[14:17], v[76:79], v[14:17], v[96:99]
	s_waitcnt lgkmcnt(0)
	v_pk_mul_f32 v[68:69], v[36:37], v[34:35]
	s_nop 2
	v_pk_mul_f32 v[66:67], v[42:43], v[54:55]
	v_pk_mul_f32 v[70:71], v[40:41], v[34:35]
	v_mfma_f32_16x16x32_bf16 v[94:97], v[72:75], v[26:29], v[120:123]
	v_mfma_f32_16x16x32_bf16 v[80:83], v[72:75], v[30:33], v[80:83]
	v_mul_f32_e64 v72, v52, v34
	v_mul_f32_e64 v73, v53, v35
	s_nop 4
	v_pk_mul_f32 v[46:47], v[94:95], v[54:55]
	v_pk_mul_f32 v[74:75], v[44:45], v[34:35]
	v_pk_mul_f32 v[52:53], v[48:49], v[34:35]
	v_pk_mul_f32 v[44:45], v[96:97], v[34:35]
	v_pk_mul_f32 v[50:51], v[80:81], v[54:55]
	v_pk_mul_f32 v[54:55], v[88:89], v[34:35]
	v_pk_mul_f32 v[48:49], v[82:83], v[34:35]
	v_rcp_f32_e32 v34, v0
	v_mfma_f32_16x16x32_bf16 v[26:29], v[76:79], v[26:29], v[124:127]
	v_fma_f32 v35, -v0, v34, 1.0
	v_fmac_f32_e32 v34, v35, v34
	v_div_scale_f32 v35, vcc, 1.0, v84, 1.0
	v_mul_f32_e32 v36, v35, v34
	v_fma_f32 v37, -v0, v36, v35
	v_fmac_f32_e32 v36, v37, v34
	v_fma_f32 v0, -v0, v36, v35
	v_div_fmas_f32 v0, v0, v34, v36
	v_div_fixup_f32 v0, v0, v84, 1.0
	ds_bpermute_b32 v42, v146, v0
	ds_bpermute_b32 v43, v147, v0
	v_mfma_f32_16x16x32_bf16 v[30:33], v[76:79], v[30:33], v[90:93]
	s_andn2_b64 vcc, exec, s[40:41]
	s_waitcnt lgkmcnt(0)
	v_pk_mul_f32 v[36:37], v[2:3], v[42:43]
	ds_bpermute_b32 v2, v144, v0
	ds_bpermute_b32 v3, v145, v0
	v_pk_mul_f32 v[34:35], v[6:7], v[42:43]
	v_pk_mul_f32 v[38:39], v[10:11], v[42:43]
	v_pk_mul_f32 v[40:41], v[14:15], v[42:43]
	v_pk_mul_f32 v[18:19], v[18:19], v[42:43]
	v_pk_mul_f32 v[22:23], v[22:23], v[42:43]
	v_pk_mul_f32 v[10:11], v[26:27], v[42:43]
	v_pk_mul_f32 v[14:15], v[30:31], v[42:43]
	s_waitcnt lgkmcnt(0)
	v_pk_mul_f32 v[26:27], v[4:5], v[2:3]
	v_pk_mul_f32 v[30:31], v[8:9], v[2:3]
	v_pk_mul_f32 v[42:43], v[12:13], v[2:3]
	v_pk_mul_f32 v[16:17], v[16:17], v[2:3]
	v_pk_mul_f32 v[8:9], v[20:21], v[2:3]
	v_pk_mul_f32 v[12:13], v[24:25], v[2:3]
	v_pk_mul_f32 v[4:5], v[28:29], v[2:3]
	v_pk_mul_f32 v[6:7], v[32:33], v[2:3]
	s_cbranch_vccnz .LBB0_1308
	v_cvt_pk_bf16_f32 v0, v60, v61
	v_cvt_pk_bf16_f32 v2, v68, v69
	ds_write2st64_b32 v129, v0, v2 offset0:108 offset1:109
	v_cvt_pk_bf16_f32 v0, v62, v63
	v_cvt_pk_bf16_f32 v2, v70, v71
	ds_write2st64_b32 v129, v0, v2 offset0:110 offset1:111
	v_cvt_pk_bf16_f32 v0, v64, v65
	v_cvt_pk_bf16_f32 v2, v72, v73
	ds_write2st64_b32 v129, v0, v2 offset0:112 offset1:113
	v_cvt_pk_bf16_f32 v0, v66, v67
	v_cvt_pk_bf16_f32 v2, v74, v75
	ds_write2st64_b32 v129, v0, v2 offset0:114 offset1:115
	v_cvt_pk_bf16_f32 v0, v56, v57
	v_cvt_pk_bf16_f32 v2, v52, v53
	ds_write2st64_b32 v129, v0, v2 offset0:116 offset1:117
	v_cvt_pk_bf16_f32 v0, v58, v59
	v_cvt_pk_bf16_f32 v2, v54, v55
	ds_write2st64_b32 v129, v0, v2 offset0:118 offset1:119
	v_cvt_pk_bf16_f32 v0, v46, v47
	v_cvt_pk_bf16_f32 v2, v44, v45
	ds_write2st64_b32 v129, v0, v2 offset0:120 offset1:121
	v_cvt_pk_bf16_f32 v0, v50, v51
	v_cvt_pk_bf16_f32 v2, v48, v49
	ds_write2st64_b32 v129, v0, v2 offset0:122 offset1:123
	v_cvt_pk_bf16_f32 v0, v36, v37
	v_cvt_pk_bf16_f32 v2, v26, v27
	ds_write2st64_b32 v129, v0, v2 offset0:124 offset1:125
	v_cvt_pk_bf16_f32 v0, v34, v35
	v_cvt_pk_bf16_f32 v2, v30, v31
	ds_write2st64_b32 v129, v0, v2 offset0:126 offset1:127
	v_cvt_pk_bf16_f32 v0, v38, v39
	v_cvt_pk_bf16_f32 v2, v42, v43
	ds_write2st64_b32 v129, v0, v2 offset0:128 offset1:129
	v_cvt_pk_bf16_f32 v0, v40, v41
	v_cvt_pk_bf16_f32 v2, v16, v17
	ds_write2st64_b32 v129, v0, v2 offset0:130 offset1:131
	v_cvt_pk_bf16_f32 v0, v18, v19
	v_cvt_pk_bf16_f32 v2, v8, v9
	ds_write2st64_b32 v129, v0, v2 offset0:132 offset1:133
	v_cvt_pk_bf16_f32 v0, v22, v23
	v_cvt_pk_bf16_f32 v2, v12, v13
	ds_write2st64_b32 v129, v0, v2 offset0:134 offset1:135
	v_cvt_pk_bf16_f32 v0, v10, v11
	v_cvt_pk_bf16_f32 v2, v4, v5
	ds_write2st64_b32 v129, v0, v2 offset0:136 offset1:137
	v_cvt_pk_bf16_f32 v0, v14, v15
	v_cvt_pk_bf16_f32 v2, v6, v7
	s_mov_b64 s[42:43], 0
	ds_write2st64_b32 v129, v0, v2 offset0:138 offset1:139
	s_branch .LBB0_1308
